# row-reduction in norm phases and final norm: 6-hop ds_bpermute butterfly replaced by permlane32/16 swap + DPP row_ror/quad_perm adds (same add order, bit-identical); modulation loads issued before the
# baseline (speedup 1.0000x reference)
; __device__ __forceinline__ unsigned cvt_pk_bf16(float lo, float hi) { const f32x2_ v = {lo, hi}; return __builtin_bit_cast(unsigned, __builtin_convertvector(v, bf16x2_)); }
; __device__ __forceinline__ float shflx(float v, int m) {
;     int lane = __builtin_amdgcn_mbcnt_hi(~0u, __builtin_amdgcn_mbcnt_lo(~0u, 0)); asm volatile("" : "+v"(lane));
;     return __int_as_float(__builtin_amdgcn_ds_bpermute((lane ^ m) << 2, __float_as_int(v)));
; }
; __device__ __forceinline__ float wave_sum(float v) {
;     v += shflx(v, 32); v += shflx(v, 16); v += shflx(v, 8); v += shflx(v, 4); v += shflx(v, 2); v += shflx(v, 1); return v;
; }
; __device__ void norm_mod_phase(const float* srcL, const float* srcC, float* cpyL, float* cpyC, const float* g, const float* mod, bf16_t* TN, int nrows, const float* pb, int nsl) {
;     ...
;         for (int j = 0; j < 4; ++j) ss += v[j][0] * v[j][0] + v[j][1] * v[j][1] + v[j][2] * v[j][2] + v[j][3] * v[j][3];
;         if (cpyL) { float* cp = lat ? cpyL + (size_t)row * 1024 : cpyC + (size_t)(row - RL) * 1024;
; #pragma unroll
;             for (int j = 0; j < 4; ++j) *(f32x4*)(cp + 256 * j + 4 * lane) = v[j]; }
;         ss = wave_sum(ss);
;         const float rstd = rsqrtf(ss * (1.0f / 1024.0f) + NEPS);
; #pragma unroll
;         for (int j = 0; j < 4; ++j) {
;             const int col = 256 * j + 4 * lane;
;             const f32x4 gg = *(const f32x4*)(g + col), sh = *(const f32x4*)(mp + col), sc = *(const f32x4*)(mp + 1024 + col);
;             float o[4];
; #pragma unroll
;             for (int e = 0; e < 4; ++e) o[e] = (v[j][e] * rstd * gg[e]) * (1.0f + sc[e]) + sh[e];
;             u32x2 w; w.x = cvt_pk_bf16(o[0], o[1]); w.y = cvt_pk_bf16(o[2], o[3]);
;             *(u32x2*)(TN + (size_t)row * 1024 + col) = w;
;         }
.LBB0_28:
	s_or_b64 exec, exec, s[2:3]
	v_min_i32_e32 v27, 0x8000, v18
	v_ashrrev_i32_e32 v27, 13, v27
	v_mul_i32_i24_e32 v36, 0x2400, v27
	v_ashrrev_i32_e32 v37, 31, v36
	v_lshl_add_u64 v[40:41], v[36:37], 2, s[6:7]
	s_mov_b64 s[2:3], 0x1000
	v_mov_b32_e32 v96, v26
	v_mov_b32_e32 v97, v0
	v_lshl_add_u64 v[98:99], v[40:41], 0, v[96:97]
	v_lshl_add_u64 v[100:101], v[98:99], 0, s[2:3]
	global_load_dwordx4 v[102:105], v[22:23], off
	global_load_dwordx4 v[60:63], v[22:23], off offset:1024
	global_load_dwordx4 v[64:67], v[22:23], off offset:2048
	global_load_dwordx4 v[68:71], v[22:23], off offset:3072
	global_load_dwordx4 v[50:53], v[98:99], off
	global_load_dwordx4 v[72:75], v[98:99], off offset:1024
	global_load_dwordx4 v[76:79], v[98:99], off offset:2048
	global_load_dwordx4 v[80:83], v[98:99], off offset:3072
	global_load_dwordx4 v[54:57], v[100:101], off
	global_load_dwordx4 v[84:87], v[100:101], off offset:1024
	global_load_dwordx4 v[88:91], v[100:101], off offset:2048
	global_load_dwordx4 v[92:95], v[100:101], off offset:3072
	s_waitcnt vmcnt(14)
	v_mov_b32_e32 v38, v11
	v_mov_b32_e32 v39, v15
	v_mov_b32_e32 v36, v10
	v_mov_b32_e32 v37, v14
	v_pk_mul_f32 v[38:39], v[38:39], v[38:39]
	s_waitcnt vmcnt(12)
	v_mov_b32_e32 v46, v3
	v_pk_fma_f32 v[36:37], v[36:37], v[36:37], v[38:39]
	v_mov_b32_e32 v38, v12
	v_mov_b32_e32 v39, v16
	v_pk_fma_f32 v[36:37], v[38:39], v[38:39], v[36:37]
	v_mov_b32_e32 v38, v13
	v_mov_b32_e32 v39, v17
	v_mov_b32_e32 v47, v7
	v_pk_fma_f32 v[36:37], v[38:39], v[38:39], v[36:37]
	v_mov_b32_e32 v38, v2
	v_mov_b32_e32 v39, v6
	v_pk_mul_f32 v[46:47], v[46:47], v[46:47]
	v_pk_fma_f32 v[38:39], v[38:39], v[38:39], v[46:47]
	v_mov_b32_e32 v46, v4
	v_mov_b32_e32 v47, v8
	v_pk_fma_f32 v[38:39], v[46:47], v[46:47], v[38:39]
	v_mov_b32_e32 v46, v5
	v_mov_b32_e32 v47, v9
	v_pk_fma_f32 v[38:39], v[46:47], v[46:47], v[38:39]
	v_add_f32_e32 v27, v36, v37
	v_mov_b32_e32 v33, v0
	v_add_f32_e32 v27, v39, v27
	v_mov_b32_e32 v35, v0
	v_add_f32_e32 v27, v38, v27
	v_lshl_add_u64 v[18:19], v[18:19], 0, s[8:9]
	v_mov_b32_e32 v31, v27
	s_nop 1
	v_permlane32_swap_b32_e32 v31, v27
	v_add_f32_e32 v27, v31, v27
	v_mov_b32_e32 v31, v27
	s_nop 1
	v_permlane16_swap_b32_e32 v31, v27
	v_add_f32_e32 v27, v31, v27
	s_nop 1
	v_add_f32_dpp v27, v27, v27 row_ror:8 row_mask:0xf bank_mask:0xf
	s_nop 1
	v_add_f32_dpp v27, v27, v27 row_ror:4 row_mask:0xf bank_mask:0xf
	s_nop 1
	v_add_f32_dpp v27, v27, v27 quad_perm:[2,3,0,1] row_mask:0xf bank_mask:0xf
	s_nop 1
	v_add_f32_dpp v27, v27, v27 quad_perm:[1,0,3,2] row_mask:0xf bank_mask:0xf
	v_fmamk_f32 v27, v27, 0x3a800000, v188
	v_cmp_gt_f32_e32 vcc, s44, v27
	v_mul_f32_e32 v31, 0x4b800000, v27
	s_nop 0
	v_cndmask_b32_e32 v27, v27, v31, vcc
	v_rsq_f32_e32 v27, v27
	s_nop 0
	v_mul_f32_e32 v31, 0x45800000, v27
	v_cndmask_b32_e32 v36, v27, v31, vcc
	v_mov_b32_e32 v27, v0
	v_pk_mul_f32 v[14:15], v[14:15], v[36:37] op_sel_hi:[1,0]
	v_pk_mul_f32 v[16:17], v[16:17], v[36:37] op_sel_hi:[1,0]
	v_mov_b32_e32 v31, v0
	v_pk_mul_f32 v[10:11], v[10:11], v[36:37] op_sel_hi:[1,0]
	v_pk_mul_f32 v[12:13], v[12:13], v[36:37] op_sel_hi:[1,0]
	v_pk_mul_f32 v[6:7], v[6:7], v[36:37] op_sel_hi:[1,0]
	v_pk_mul_f32 v[8:9], v[8:9], v[36:37] op_sel_hi:[1,0]
	v_pk_mul_f32 v[2:3], v[2:3], v[36:37] op_sel_hi:[1,0]
	v_pk_mul_f32 v[4:5], v[4:5], v[36:37] op_sel_hi:[1,0]
	v_cmp_le_i32_e32 vcc, s0, v18
	s_or_b64 s[12:13], vcc, s[12:13]
	s_waitcnt vmcnt(0)
	v_pk_mul_f32 v[14:15], v[102:103], v[14:15]
	v_pk_mul_f32 v[16:17], v[104:105], v[16:17]
	v_pk_add_f32 v[46:47], v[54:55], 1.0 op_sel_hi:[1,0]
	s_nop 0
	v_pk_fma_f32 v[14:15], v[46:47], v[14:15], v[50:51]
	v_pk_add_f32 v[46:47], v[56:57], 1.0 op_sel_hi:[1,0]
	v_cvt_pk_bf16_f32 v14, v14, v15
	v_pk_fma_f32 v[16:17], v[46:47], v[16:17], v[52:53]
	s_nop 0
	v_cvt_pk_bf16_f32 v15, v16, v17
	global_store_dwordx2 v[24:25], v[14:15], off
	v_pk_mul_f32 v[10:11], v[60:61], v[10:11]
	v_pk_mul_f32 v[12:13], v[62:63], v[12:13]
	v_pk_add_f32 v[14:15], v[84:85], 1.0 op_sel_hi:[1,0]
	s_nop 0
	v_pk_fma_f32 v[10:11], v[14:15], v[10:11], v[72:73]
	v_pk_add_f32 v[14:15], v[86:87], 1.0 op_sel_hi:[1,0]
	v_cvt_pk_bf16_f32 v10, v10, v11
	v_pk_fma_f32 v[12:13], v[14:15], v[12:13], v[74:75]
	s_nop 0
	v_cvt_pk_bf16_f32 v11, v12, v13
	global_store_dwordx2 v[24:25], v[10:11], off offset:512
	v_pk_mul_f32 v[6:7], v[64:65], v[6:7]
	v_pk_mul_f32 v[8:9], v[66:67], v[8:9]
	v_pk_add_f32 v[10:11], v[88:89], 1.0 op_sel_hi:[1,0]
	s_nop 0
	v_pk_fma_f32 v[6:7], v[6:7], v[10:11], v[76:77]
	v_pk_add_f32 v[10:11], v[90:91], 1.0 op_sel_hi:[1,0]
	v_cvt_pk_bf16_f32 v6, v6, v7
	v_pk_fma_f32 v[8:9], v[8:9], v[10:11], v[78:79]
	s_nop 0
	v_cvt_pk_bf16_f32 v7, v8, v9
	global_store_dwordx2 v[24:25], v[6:7], off offset:1024
	v_pk_mul_f32 v[2:3], v[2:3], v[68:69]
	v_pk_mul_f32 v[4:5], v[4:5], v[70:71]
	v_pk_add_f32 v[6:7], v[92:93], 1.0 op_sel_hi:[1,0]
	s_nop 0
	v_pk_fma_f32 v[2:3], v[2:3], v[6:7], v[80:81]
	v_pk_add_f32 v[6:7], v[94:95], 1.0 op_sel_hi:[1,0]
	v_cvt_pk_bf16_f32 v2, v2, v3
	v_pk_fma_f32 v[4:5], v[4:5], v[6:7], v[82:83]
	s_nop 0
	v_cvt_pk_bf16_f32 v3, v4, v5
	global_store_dwordx2 v[24:25], v[2:3], off offset:1536
	v_lshl_add_u64 v[24:25], v[24:25], 0, s[10:11]
	s_andn2_b64 exec, exec, s[12:13]
	s_cbranch_execz .LBB0_31

; __device__ __forceinline__ unsigned cvt_pk_bf16(float lo, float hi) { const f32x2_ v = {lo, hi}; return __builtin_bit_cast(unsigned, __builtin_convertvector(v, bf16x2_)); }
; __device__ __forceinline__ float shflx(float v, int m) {
;     int lane = __builtin_amdgcn_mbcnt_hi(~0u, __builtin_amdgcn_mbcnt_lo(~0u, 0)); asm volatile("" : "+v"(lane));
;     return __int_as_float(__builtin_amdgcn_ds_bpermute((lane ^ m) << 2, __float_as_int(v)));
; }
; __device__ __forceinline__ float wave_sum(float v) {
;     v += shflx(v, 32); v += shflx(v, 16); v += shflx(v, 8); v += shflx(v, 4); v += shflx(v, 2); v += shflx(v, 1); return v;
; }
; __device__ void norm_mod_phase(const float* srcL, const float* srcC, float* cpyL, float* cpyC, const float* g, const float* mod, bf16_t* TN, int nrows, const float* pb, int nsl) {
;     ...
;         for (int j = 0; j < 4; ++j) ss += v[j][0] * v[j][0] + v[j][1] * v[j][1] + v[j][2] * v[j][2] + v[j][3] * v[j][3];
;         if (cpyL) { float* cp = lat ? cpyL + (size_t)row * 1024 : cpyC + (size_t)(row - RL) * 1024;
; #pragma unroll
;             for (int j = 0; j < 4; ++j) *(f32x4*)(cp + 256 * j + 4 * lane) = v[j]; }
;         ss = wave_sum(ss);
;         const float rstd = rsqrtf(ss * (1.0f / 1024.0f) + NEPS);
; #pragma unroll
;         for (int j = 0; j < 4; ++j) {
;             const int col = 256 * j + 4 * lane;
;             const f32x4 gg = *(const f32x4*)(g + col), sh = *(const f32x4*)(mp + col), sc = *(const f32x4*)(mp + 1024 + col);
;             float o[4];
; #pragma unroll
;             for (int e = 0; e < 4; ++e) o[e] = (v[j][e] * rstd * gg[e]) * (1.0f + sc[e]) + sh[e];
;             u32x2 w; w.x = cvt_pk_bf16(o[0], o[1]); w.y = cvt_pk_bf16(o[2], o[3]);
;             *(u32x2*)(TN + (size_t)row * 1024 + col) = w;
;         }
.LBB0_532:
	s_or_b64 exec, exec, s[2:3]
	v_min_i32_e32 v1, 0x8000, v18
	v_ashrrev_i32_e32 v1, 13, v1
	v_mul_i32_i24_e32 v34, 0x2400, v1
	v_ashrrev_i32_e32 v35, 31, v34
	v_lshl_add_u64 v[38:39], v[34:35], 2, s[8:9]
	s_mov_b64 s[2:3], 0x1000
	v_lshl_add_u64 v[36:37], v[38:39], 0, s[2:3]
	v_lshl_add_u64 v[38:39], v[38:39], 0, v[26:27]
	v_lshl_add_u64 v[48:49], v[36:37], 0, v[26:27]
	global_load_dwordx4 v[96:99], v[22:23], off
	global_load_dwordx4 v[44:47], v[38:39], off
	global_load_dwordx4 v[60:63], v[22:23], off offset:1024
	global_load_dwordx4 v[64:67], v[22:23], off offset:2048
	global_load_dwordx4 v[68:71], v[22:23], off offset:3072
	global_load_dwordx4 v[72:75], v[38:39], off offset:1024
	global_load_dwordx4 v[76:79], v[38:39], off offset:2048
	global_load_dwordx4 v[80:83], v[38:39], off offset:3072
	global_load_dwordx4 v[84:87], v[48:49], off offset:1024
	global_load_dwordx4 v[88:91], v[48:49], off offset:2048
	global_load_dwordx4 v[92:95], v[48:49], off offset:3072
	global_load_dwordx4 v[48:51], v[48:49], off
	s_waitcnt vmcnt(14)
	v_mov_b32_e32 v36, v7
	v_mov_b32_e32 v37, v11
	v_mov_b32_e32 v34, v6
	v_mov_b32_e32 v35, v10
	v_pk_mul_f32 v[36:37], v[36:37], v[36:37]
	s_waitcnt vmcnt(12)
	v_mov_b32_e32 v40, v15
	v_pk_fma_f32 v[34:35], v[34:35], v[34:35], v[36:37]
	v_mov_b32_e32 v36, v8
	v_mov_b32_e32 v37, v12
	v_pk_fma_f32 v[34:35], v[36:37], v[36:37], v[34:35]
	v_mov_b32_e32 v36, v9
	v_mov_b32_e32 v37, v13
	v_mov_b32_e32 v41, v3
	v_pk_fma_f32 v[34:35], v[36:37], v[36:37], v[34:35]
	v_mov_b32_e32 v36, v14
	v_mov_b32_e32 v37, v2
	v_pk_mul_f32 v[40:41], v[40:41], v[40:41]
	v_pk_fma_f32 v[36:37], v[36:37], v[36:37], v[40:41]
	v_mov_b32_e32 v40, v16
	v_mov_b32_e32 v41, v4
	v_pk_fma_f32 v[36:37], v[40:41], v[40:41], v[36:37]
	v_mov_b32_e32 v40, v17
	v_mov_b32_e32 v41, v5
	v_pk_fma_f32 v[36:37], v[40:41], v[40:41], v[36:37]
	v_add_f32_e32 v1, v34, v35
	v_mov_b32_e32 v31, v0
	v_add_f32_e32 v1, v37, v1
	v_mov_b32_e32 v33, v0
	v_add_f32_e32 v1, v36, v1
	v_lshl_add_u64 v[18:19], v[18:19], 0, s[10:11]
	v_mov_b32_e32 v29, v1
	s_nop 1
	v_permlane32_swap_b32_e32 v29, v1
	v_add_f32_e32 v1, v29, v1
	v_mov_b32_e32 v29, v1
	s_nop 1
	v_permlane16_swap_b32_e32 v29, v1
	v_add_f32_e32 v1, v29, v1
	s_nop 1
	v_add_f32_dpp v1, v1, v1 row_ror:8 row_mask:0xf bank_mask:0xf
	s_nop 1
	v_add_f32_dpp v1, v1, v1 row_ror:4 row_mask:0xf bank_mask:0xf
	s_nop 1
	v_add_f32_dpp v1, v1, v1 quad_perm:[2,3,0,1] row_mask:0xf bank_mask:0xf
	s_nop 1
	v_add_f32_dpp v1, v1, v1 quad_perm:[1,0,3,2] row_mask:0xf bank_mask:0xf
	v_fmamk_f32 v1, v1, 0x3a800000, v188
	v_cmp_gt_f32_e32 vcc, s44, v1
	v_mul_f32_e32 v29, 0x4b800000, v1
	s_nop 0
	v_cndmask_b32_e32 v1, v1, v29, vcc
	v_rsq_f32_e32 v1, v1
	s_nop 0
	v_mul_f32_e32 v29, 0x45800000, v1
	v_cndmask_b32_e32 v34, v1, v29, vcc
	v_pk_mul_f32 v[10:11], v[10:11], v[34:35] op_sel_hi:[1,0]
	v_pk_mul_f32 v[12:13], v[12:13], v[34:35] op_sel_hi:[1,0]
	v_mov_b32_e32 v29, v0
	v_pk_mul_f32 v[6:7], v[6:7], v[34:35] op_sel_hi:[1,0]
	v_pk_mul_f32 v[8:9], v[8:9], v[34:35] op_sel_hi:[1,0]
	v_pk_mul_f32 v[2:3], v[2:3], v[34:35] op_sel_hi:[1,0]
	v_pk_mul_f32 v[4:5], v[4:5], v[34:35] op_sel_hi:[1,0]
	v_pk_mul_f32 v[14:15], v[14:15], v[34:35] op_sel_hi:[1,0]
	v_cmp_lt_i32_e32 vcc, s45, v18
	s_or_b64 s[14:15], vcc, s[14:15]
	s_waitcnt vmcnt(0)
	v_pk_mul_f32 v[10:11], v[96:97], v[10:11]
	v_pk_mul_f32 v[12:13], v[98:99], v[12:13]
	v_pk_add_f32 v[40:41], v[48:49], 1.0 op_sel_hi:[1,0]
	s_nop 0
	v_pk_fma_f32 v[10:11], v[40:41], v[10:11], v[44:45]
	v_pk_add_f32 v[40:41], v[50:51], 1.0 op_sel_hi:[1,0]
	v_cvt_pk_bf16_f32 v10, v10, v11
	v_pk_fma_f32 v[12:13], v[40:41], v[12:13], v[46:47]
	s_nop 0
	v_cvt_pk_bf16_f32 v11, v12, v13
	global_store_dwordx2 v[24:25], v[10:11], off
	v_pk_mul_f32 v[6:7], v[60:61], v[6:7]
	v_pk_mul_f32 v[8:9], v[62:63], v[8:9]
	v_pk_add_f32 v[10:11], v[84:85], 1.0 op_sel_hi:[1,0]
	s_nop 0
	v_pk_fma_f32 v[6:7], v[10:11], v[6:7], v[72:73]
	v_pk_add_f32 v[10:11], v[86:87], 1.0 op_sel_hi:[1,0]
	v_cvt_pk_bf16_f32 v6, v6, v7
	v_pk_fma_f32 v[8:9], v[10:11], v[8:9], v[74:75]
	s_nop 0
	v_cvt_pk_bf16_f32 v7, v8, v9
	global_store_dwordx2 v[24:25], v[6:7], off offset:512
	v_pk_mul_f32 v[2:3], v[64:65], v[2:3]
	v_pk_mul_f32 v[4:5], v[66:67], v[4:5]
	v_pk_add_f32 v[6:7], v[88:89], 1.0 op_sel_hi:[1,0]
	s_nop 0
	v_pk_fma_f32 v[2:3], v[2:3], v[6:7], v[76:77]
	v_pk_add_f32 v[6:7], v[90:91], 1.0 op_sel_hi:[1,0]
	v_cvt_pk_bf16_f32 v2, v2, v3
	v_pk_fma_f32 v[4:5], v[4:5], v[6:7], v[78:79]
	s_nop 0
	v_cvt_pk_bf16_f32 v3, v4, v5
	global_store_dwordx2 v[24:25], v[2:3], off offset:1024
	v_pk_mul_f32 v[2:3], v[14:15], v[68:69]
	v_pk_add_f32 v[10:11], v[92:93], 1.0 op_sel_hi:[1,0]
	s_nop 0
	v_pk_fma_f32 v[2:3], v[2:3], v[10:11], v[80:81]
	v_pk_mul_f32 v[6:7], v[16:17], v[34:35] op_sel_hi:[1,0]
	v_cvt_pk_bf16_f32 v2, v2, v3
	v_pk_mul_f32 v[4:5], v[6:7], v[70:71]
	v_pk_add_f32 v[6:7], v[94:95], 1.0 op_sel_hi:[1,0]
	s_nop 0
	v_pk_fma_f32 v[4:5], v[4:5], v[6:7], v[82:83]
	s_nop 0
	v_cvt_pk_bf16_f32 v3, v4, v5
	global_store_dwordx2 v[24:25], v[2:3], off offset:1536
	v_lshl_add_u64 v[24:25], v[24:25], 0, s[12:13]
	s_andn2_b64 exec, exec, s[14:15]
	s_cbranch_execz .LBB0_535

; __device__ __forceinline__ unsigned cvt_pk_bf16(float lo, float hi) { const f32x2_ v = {lo, hi}; return __builtin_bit_cast(unsigned, __builtin_convertvector(v, bf16x2_)); }
; __device__ __forceinline__ float shflx(float v, int m) {
;     int lane = __builtin_amdgcn_mbcnt_hi(~0u, __builtin_amdgcn_mbcnt_lo(~0u, 0)); asm volatile("" : "+v"(lane));
;     return __int_as_float(__builtin_amdgcn_ds_bpermute((lane ^ m) << 2, __float_as_int(v)));
; }
; __device__ __forceinline__ float wave_sum(float v) {
;     v += shflx(v, 32); v += shflx(v, 16); v += shflx(v, 8); v += shflx(v, 4); v += shflx(v, 2); v += shflx(v, 1); return v;
; }
; __device__ void norm_mod_phase(const float* srcL, const float* srcC, float* cpyL, float* cpyC, const float* g, const float* mod, bf16_t* TN, int nrows, const float* pb, int nsl) {
;     ...
;         for (int j = 0; j < 4; ++j) ss += v[j][0] * v[j][0] + v[j][1] * v[j][1] + v[j][2] * v[j][2] + v[j][3] * v[j][3];
;         if (cpyL) { float* cp = lat ? cpyL + (size_t)row * 1024 : cpyC + (size_t)(row - RL) * 1024;
; #pragma unroll
;             for (int j = 0; j < 4; ++j) *(f32x4*)(cp + 256 * j + 4 * lane) = v[j]; }
;         ss = wave_sum(ss);
;         const float rstd = rsqrtf(ss * (1.0f / 1024.0f) + NEPS);
; #pragma unroll
;         for (int j = 0; j < 4; ++j) {
;             const int col = 256 * j + 4 * lane;
;             const f32x4 gg = *(const f32x4*)(g + col), sh = *(const f32x4*)(mp + col), sc = *(const f32x4*)(mp + 1024 + col);
;             float o[4];
; #pragma unroll
;             for (int e = 0; e < 4; ++e) o[e] = (v[j][e] * rstd * gg[e]) * (1.0f + sc[e]) + sh[e];
;             u32x2 w; w.x = cvt_pk_bf16(o[0], o[1]); w.y = cvt_pk_bf16(o[2], o[3]);
;             *(u32x2*)(TN + (size_t)row * 1024 + col) = w;
;         }
.LBB0_634:
	s_or_b64 exec, exec, s[2:3]
	v_min_i32_e32 v1, 0x8000, v18
	v_ashrrev_i32_e32 v1, 13, v1
	v_mul_i32_i24_e32 v34, 0x2400, v1
	v_ashrrev_i32_e32 v35, 31, v34
	v_lshl_add_u64 v[38:39], v[34:35], 2, s[10:11]
	s_waitcnt vmcnt(2)
	v_mov_b32_e32 v36, v7
	v_mov_b32_e32 v37, v11
	s_mov_b64 s[2:3], 0x1000
	v_mov_b32_e32 v34, v6
	v_mov_b32_e32 v35, v10
	v_pk_mul_f32 v[36:37], v[36:37], v[36:37]
	v_lshl_add_u64 v[50:51], v[38:39], 0, s[2:3]
	v_pk_fma_f32 v[34:35], v[34:35], v[34:35], v[36:37]
	v_mov_b32_e32 v36, v8
	v_mov_b32_e32 v37, v12
	v_mov_b32_e32 v1, v220
	v_mov_b32_e32 v29, v220
	v_mov_b32_e32 v31, v220
	v_mov_b32_e32 v33, v220
	v_mov_b32_e32 v56, v220
	v_mov_b32_e32 v57, v220
	v_lshl_add_u64 v[52:53], v[38:39], 0, v[26:27]
	v_lshl_add_u64 v[42:43], v[50:51], 0, v[26:27]
	v_pk_fma_f32 v[46:47], v[36:37], v[36:37], v[34:35]
	global_load_dwordx4 v[34:37], v[22:23], off
	global_load_dwordx4 v[38:41], v[52:53], off
	global_load_dwordx4 v[60:63], v[22:23], off offset:1024
	global_load_dwordx4 v[64:67], v[22:23], off offset:2048
	global_load_dwordx4 v[68:71], v[22:23], off offset:3072
	global_load_dwordx4 v[72:75], v[52:53], off offset:1024
	global_load_dwordx4 v[76:79], v[52:53], off offset:2048
	global_load_dwordx4 v[80:83], v[52:53], off offset:3072
	global_load_dwordx4 v[84:87], v[42:43], off offset:1024
	global_load_dwordx4 v[88:91], v[42:43], off offset:2048
	global_load_dwordx4 v[92:95], v[42:43], off offset:3072
	s_nop 0
	global_load_dwordx4 v[42:45], v[42:43], off
	v_mov_b32_e32 v48, v9
	v_mov_b32_e32 v49, v13
	s_waitcnt vmcnt(12)
	v_mov_b32_e32 v54, v15
	v_mov_b32_e32 v55, v3
	v_pk_fma_f32 v[46:47], v[48:49], v[48:49], v[46:47]
	v_mov_b32_e32 v48, v14
	v_mov_b32_e32 v49, v2
	v_pk_mul_f32 v[54:55], v[54:55], v[54:55]
	v_add_f32_e32 v27, v46, v47
	v_pk_fma_f32 v[48:49], v[48:49], v[48:49], v[54:55]
	v_mov_b32_e32 v54, v16
	v_mov_b32_e32 v55, v4
	v_pk_fma_f32 v[48:49], v[54:55], v[54:55], v[48:49]
	v_mov_b32_e32 v54, v17
	v_mov_b32_e32 v55, v5
	v_pk_fma_f32 v[48:49], v[54:55], v[54:55], v[48:49]
	v_add_f32_e32 v27, v49, v27
	v_add_f32_e32 v27, v48, v27
	v_lshl_add_u64 v[18:19], v[18:19], 0, s[12:13]
	v_mov_b32_e32 v29, v0
	v_mov_b32_e32 v31, v0
	v_mov_b32_e32 v33, v0
	v_mov_b32_e32 v1, v27
	s_nop 1
	v_permlane32_swap_b32_e32 v1, v27
	v_add_f32_e32 v1, v27, v1
	v_mov_b32_e32 v27, v1
	s_nop 1
	v_permlane16_swap_b32_e32 v27, v1
	v_add_f32_e32 v1, v27, v1
	s_nop 1
	v_add_f32_dpp v1, v1, v1 row_ror:8 row_mask:0xf bank_mask:0xf
	s_nop 1
	v_add_f32_dpp v1, v1, v1 row_ror:4 row_mask:0xf bank_mask:0xf
	s_nop 1
	v_add_f32_dpp v1, v1, v1 quad_perm:[2,3,0,1] row_mask:0xf bank_mask:0xf
	s_nop 1
	v_add_f32_dpp v1, v1, v1 quad_perm:[1,0,3,2] row_mask:0xf bank_mask:0xf
	v_fmamk_f32 v1, v1, 0x3a800000, v188
	v_mul_f32_e32 v27, 0x4b800000, v1
	v_cmp_gt_f32_e32 vcc, s44, v1
	s_nop 1
	v_cndmask_b32_e32 v1, v1, v27, vcc
	v_rsq_f32_e32 v1, v1
	s_nop 0
	v_mul_f32_e32 v27, 0x45800000, v1
	v_cndmask_b32_e32 v46, v1, v27, vcc
	v_pk_mul_f32 v[10:11], v[10:11], v[46:47] op_sel_hi:[1,0]
	v_pk_mul_f32 v[12:13], v[12:13], v[46:47] op_sel_hi:[1,0]
	s_waitcnt vmcnt(0)
	v_pk_mul_f32 v[10:11], v[34:35], v[10:11]
	v_pk_mul_f32 v[12:13], v[36:37], v[12:13]
	v_pk_add_f32 v[34:35], v[42:43], 1.0 op_sel_hi:[1,0]
	v_pk_add_f32 v[36:37], v[44:45], 1.0 op_sel_hi:[1,0]
	v_pk_fma_f32 v[10:11], v[34:35], v[10:11], v[38:39]
	v_pk_fma_f32 v[12:13], v[36:37], v[12:13], v[40:41]
	v_cvt_pk_bf16_f32 v10, v10, v11
	v_cvt_pk_bf16_f32 v11, v12, v13
	global_store_dwordx2 v[24:25], v[10:11], off
	v_pk_mul_f32 v[6:7], v[6:7], v[46:47] op_sel_hi:[1,0]
	v_pk_mul_f32 v[8:9], v[8:9], v[46:47] op_sel_hi:[1,0]
	v_pk_mul_f32 v[2:3], v[2:3], v[46:47] op_sel_hi:[1,0]
	v_pk_mul_f32 v[4:5], v[4:5], v[46:47] op_sel_hi:[1,0]
	v_pk_mul_f32 v[14:15], v[14:15], v[46:47] op_sel_hi:[1,0]
	v_pk_mul_f32 v[16:17], v[16:17], v[46:47] op_sel_hi:[1,0]
	v_cmp_lt_i32_e32 vcc, s45, v18
	s_or_b64 s[16:17], vcc, s[16:17]
	v_pk_mul_f32 v[6:7], v[60:61], v[6:7]
	v_pk_add_f32 v[10:11], v[84:85], 1.0 op_sel_hi:[1,0]
	v_pk_mul_f32 v[8:9], v[62:63], v[8:9]
	v_pk_add_f32 v[12:13], v[86:87], 1.0 op_sel_hi:[1,0]
	v_pk_fma_f32 v[6:7], v[10:11], v[6:7], v[72:73]
	v_pk_fma_f32 v[8:9], v[12:13], v[8:9], v[74:75]
	v_cvt_pk_bf16_f32 v6, v6, v7
	v_cvt_pk_bf16_f32 v7, v8, v9
	global_store_dwordx2 v[24:25], v[6:7], off offset:512
	v_pk_mul_f32 v[2:3], v[64:65], v[2:3]
	v_pk_add_f32 v[6:7], v[88:89], 1.0 op_sel_hi:[1,0]
	v_pk_mul_f32 v[4:5], v[66:67], v[4:5]
	v_pk_add_f32 v[8:9], v[90:91], 1.0 op_sel_hi:[1,0]
	v_pk_fma_f32 v[2:3], v[2:3], v[6:7], v[76:77]
	v_pk_fma_f32 v[4:5], v[4:5], v[8:9], v[78:79]
	v_cvt_pk_bf16_f32 v2, v2, v3
	v_cvt_pk_bf16_f32 v3, v4, v5
	global_store_dwordx2 v[24:25], v[2:3], off offset:1024
	v_pk_mul_f32 v[2:3], v[14:15], v[68:69]
	v_pk_add_f32 v[6:7], v[92:93], 1.0 op_sel_hi:[1,0]
	v_pk_mul_f32 v[4:5], v[16:17], v[70:71]
	v_pk_add_f32 v[8:9], v[94:95], 1.0 op_sel_hi:[1,0]
	v_pk_fma_f32 v[2:3], v[2:3], v[6:7], v[80:81]
	v_pk_fma_f32 v[4:5], v[4:5], v[8:9], v[82:83]
	v_cvt_pk_bf16_f32 v2, v2, v3
	v_cvt_pk_bf16_f32 v3, v4, v5
	global_store_dwordx2 v[24:25], v[2:3], off offset:1536
	v_lshl_add_u64 v[24:25], v[24:25], 0, s[14:15]
	s_andn2_b64 exec, exec, s[16:17]
	s_cbranch_execz .LBB0_637

; __device__ __forceinline__ int opaque_tid() { int t = threadIdx.x; asm volatile("" : "+v"(t)); return t; }
; __device__ __forceinline__ int opaque_bid() { int t = blockIdx.x; asm volatile("" : "+s"(t)); return t; }
; __device__ __forceinline__ int opaque_gdim() { int t = gridDim.x; asm volatile("" : "+s"(t)); return t; }
; __device__ __forceinline__ float shflx(float v, int m) {
;     int lane = __builtin_amdgcn_mbcnt_hi(~0u, __builtin_amdgcn_mbcnt_lo(~0u, 0)); asm volatile("" : "+v"(lane));
;     return __int_as_float(__builtin_amdgcn_ds_bpermute((lane ^ m) << 2, __float_as_int(v)));
; }
; __device__ __forceinline__ float wave_sum(float v) {
;     v += shflx(v, 32); v += shflx(v, 16); v += shflx(v, 8); v += shflx(v, 4); v += shflx(v, 2); v += shflx(v, 1); return v;
; }
; __device__ void final_norm_phase(float* H, const float* g) {
;     const int tid_ = opaque_tid(); const int lane = tid_ & 63, gw = opaque_bid() * 8 + (tid_ >> 6), nw = opaque_gdim() * 8;
;     for (int row = gw; row < RL; row += nw) {
;         float* sp = H + (size_t)row * 1024; f32x4 v[4]; float ss = 0.f;
; #pragma unroll
;         for (int j = 0; j < 4; ++j) { v[j] = *(const f32x4*)(sp + 256 * j + 4 * lane); ss += v[j][0] * v[j][0] + v[j][1] * v[j][1] + v[j][2] * v[j][2] + v[j][3] * v[j][3]; }
;         ss = wave_sum(ss);
;         const float rstd = rsqrtf(ss * (1.0f / 1024.0f) + NEPS);
; #pragma unroll
;         for (int j = 0; j < 4; ++j) { const f32x4 gg = *(const f32x4*)(g + 256 * j + 4 * lane); *(f32x4*)(sp + 256 * j + 4 * lane) = v[j] * rstd * gg; }
;     }
; }
.LBB0_850:
	global_load_dwordx4 v[8:11], v[6:7], off offset:-3072
	global_load_dwordx4 v[12:15], v[6:7], off offset:-2048
	global_load_dwordx4 v[16:19], v[6:7], off offset:-1024
	global_load_dwordx4 v[20:23], v[6:7], off
	v_mov_b32_e32 v1, v220
	v_mov_b32_e32 v3, v220
	v_mov_b32_e32 v44, v220
	v_mov_b32_e32 v45, v220
	v_mov_b32_e32 v46, v220
	v_mov_b32_e32 v47, v220
	global_load_dwordx4 v[24:27], v[4:5], off
	global_load_dwordx4 v[60:63], v[4:5], off offset:1024
	global_load_dwordx4 v[64:67], v[4:5], off offset:2048
	global_load_dwordx4 v[68:71], v[4:5], off offset:3072
	v_lshlrev_b32_e32 v1, 2, v1
	v_xor_b32_e32 v1, 0x80, v1
	v_lshlrev_b32_e32 v3, 2, v3
	v_xor_b32_e32 v3, 64, v3
	v_add_u32_e32 v2, s4, v2
	s_waitcnt vmcnt(7)
	v_mov_b32_e32 v30, v9
	s_waitcnt vmcnt(6)
	v_mov_b32_e32 v31, v13
	v_mov_b32_e32 v28, v8
	v_mov_b32_e32 v29, v12
	s_waitcnt vmcnt(5)
	v_mov_b32_e32 v38, v17
	s_waitcnt vmcnt(4)
	v_mov_b32_e32 v39, v21
	v_pk_mul_f32 v[30:31], v[30:31], v[30:31]
	v_mov_b32_e32 v32, v10
	v_mov_b32_e32 v33, v14
	v_mov_b32_e32 v36, v16
	v_mov_b32_e32 v37, v20
	v_pk_mul_f32 v[38:39], v[38:39], v[38:39]
	v_pk_fma_f32 v[28:29], v[28:29], v[28:29], v[30:31]
	v_mov_b32_e32 v34, v11
	v_mov_b32_e32 v35, v15
	v_mov_b32_e32 v40, v18
	v_mov_b32_e32 v41, v22
	v_pk_fma_f32 v[30:31], v[36:37], v[36:37], v[38:39]
	v_pk_fma_f32 v[28:29], v[32:33], v[32:33], v[28:29]
	v_mov_b32_e32 v42, v19
	v_mov_b32_e32 v43, v23
	v_pk_fma_f32 v[30:31], v[40:41], v[40:41], v[30:31]
	v_pk_fma_f32 v[28:29], v[34:35], v[34:35], v[28:29]
	v_pk_fma_f32 v[30:31], v[42:43], v[42:43], v[30:31]
	v_add_f32_e32 v28, v28, v29
	v_add_f32_e32 v28, v28, v30
	v_add_f32_e32 v28, v28, v31
	v_mov_b32_e32 v1, v28
	s_nop 1
	v_permlane32_swap_b32_e32 v1, v28
	v_add_f32_e32 v1, v28, v1
	v_mov_b32_e32 v3, v1
	s_nop 1
	v_permlane16_swap_b32_e32 v3, v1
	v_add_f32_e32 v1, v1, v3
	s_nop 1
	v_add_f32_dpp v1, v1, v1 row_ror:8 row_mask:0xf bank_mask:0xf
	s_nop 1
	v_add_f32_dpp v1, v1, v1 row_ror:4 row_mask:0xf bank_mask:0xf
	s_nop 1
	v_add_f32_dpp v1, v1, v1 quad_perm:[2,3,0,1] row_mask:0xf bank_mask:0xf
	s_nop 1
	v_add_f32_dpp v1, v1, v1 quad_perm:[1,0,3,2] row_mask:0xf bank_mask:0xf
	v_fmamk_f32 v1, v1, 0x3a800000, v188
	v_mul_f32_e32 v3, 0x4b800000, v1
	v_cmp_gt_f32_e32 vcc, s44, v1
	s_nop 1
	v_cndmask_b32_e32 v1, v1, v3, vcc
	v_rsq_f32_e32 v1, v1
	s_nop 0
	v_mul_f32_e32 v3, 0x45800000, v1
	v_cndmask_b32_e32 v28, v1, v3, vcc
	v_pk_mul_f32 v[8:9], v[8:9], v[28:29] op_sel_hi:[1,0]
	v_pk_mul_f32 v[10:11], v[10:11], v[28:29] op_sel_hi:[1,0]
	s_waitcnt vmcnt(0)
	v_pk_mul_f32 v[8:9], v[24:25], v[8:9]
	v_pk_mul_f32 v[10:11], v[26:27], v[10:11]
	global_store_dwordx4 v[6:7], v[8:11], off offset:-3072
	v_pk_mul_f32 v[14:15], v[14:15], v[28:29] op_sel_hi:[1,0]
	v_pk_mul_f32 v[12:13], v[12:13], v[28:29] op_sel_hi:[1,0]
	v_cmp_lt_i32_e32 vcc, s57, v2
	s_or_b64 s[8:9], vcc, s[8:9]
	v_pk_mul_f32 v[8:9], v[60:61], v[12:13]
	v_pk_mul_f32 v[10:11], v[62:63], v[14:15]
	global_store_dwordx4 v[6:7], v[8:11], off offset:-2048
	v_pk_mul_f32 v[12:13], v[18:19], v[28:29] op_sel_hi:[1,0]
	v_pk_mul_f32 v[14:15], v[16:17], v[28:29] op_sel_hi:[1,0]
	s_nop 1
	v_pk_mul_f32 v[10:11], v[66:67], v[12:13]
	v_pk_mul_f32 v[8:9], v[64:65], v[14:15]
	global_store_dwordx4 v[6:7], v[8:11], off offset:-1024
	v_pk_mul_f32 v[12:13], v[22:23], v[28:29] op_sel_hi:[1,0]
	v_pk_mul_f32 v[14:15], v[20:21], v[28:29] op_sel_hi:[1,0]
	s_nop 1
	v_pk_mul_f32 v[10:11], v[70:71], v[12:13]
	v_pk_mul_f32 v[8:9], v[68:69], v[14:15]
	global_store_dwordx4 v[6:7], v[8:11], off
	v_lshl_add_u64 v[6:7], v[6:7], 0, s[6:7]
	s_andn2_b64 exec, exec, s[8:9]
	s_cbranch_execnz .LBB0_850
